# s13 + attention: second barrier per KV tile removed (with the K half written before the first barrier, that barrier already orders every LDS hand-off)
# speedup vs baseline: 1.0054x; 1.0034x over previous
; #define SBAR() __builtin_amdgcn_sched_barrier(0)
; #define SLOAD(i, k0) do { sr_[i].vs0 = St::ld8(&Vh[(long)((k0) + sr) * LDK + sc]); sr_[i].vs1 = St::ld8(&Vh[(long)((k0) + 32 + sr) * LDK + sc]); \
;     sr_[i].ks0 = St::ld8(&Kh[(long)((k0) + sr) * LDK + sc]); sr_[i].ks1 = St::ld8(&Kh[(long)((k0) + 32 + sr) * LDK + sc]); } while (0)
; __device__ __forceinline__ void partialSM(f32x16& p0, f32x16& p1, float& m_reg, float& mn, float& alpha) {
;     ...
;   for (int r = 0; r < 16; ++r) p0[r] = fmaf(p0[r], C, mnC); for (int r = 0; r < 16; ++r) p1[r] = fmaf(p1[r], C, mnC);
;   for (int r = 0; r < 16; ++r) p0[r] = __builtin_amdgcn_exp2f(p0[r]);
; }
; __device__ __forceinline__ void finishSM(f32x16& p0, f32x16& p1, float alpha, float& l_reg, bf16x8& pa0, bf16x8& pa1, bf16x8& pa2, bf16x8& pa3) {
;   for (int r = 0; r < 16; ++r) p1[r] = __builtin_amdgcn_exp2f(p1[r]);
;   float ps = 0; for (int r = 0; r < 16; ++r) ps += p0[r]; for (int r = 0; r < 16; ++r) ps += p1[r];
;   { auto rr = __builtin_amdgcn_permlane32_swap(__float_as_uint(ps), __float_as_uint(ps), false, false);
;     ps = __uint_as_float(rr[0]) + __uint_as_float(rr[1]); }
;   l_reg = l_reg * alpha + ps;
;     ...
;   PK4(p0, 0, pa0); PK4(p0, 8, pa1); PK4(p1, 0, pa2); PK4(p1, 8, pa3);
;     ...
; }
; __device__ __forceinline__ void qkt(f32x16& p0, f32x16& p1, const bf16* Ks, const bf16x8* qr, int r32, int hi) {
;   p0 = f32x16{}; p1 = f32x16{};
;   for (int d0 = 0; d0 < 8; ++d0) { int cb = (d0 * 16 + hi * 8) * 2;
;     bf16x8 b0 = *reinterpret_cast<const bf16x8*>((const char*)Ks + KSWZ(r32, cb));
;     bf16x8 b1 = *reinterpret_cast<const bf16x8*>((const char*)Ks + KSWZ(32 + r32, cb));
;     p0 = __builtin_amdgcn_mfma_f32_32x32x16_bf16(b0, qr[d0], p0, 0, 0, 0);
;     p1 = __builtin_amdgcn_mfma_f32_32x32x16_bf16(b1, qr[d0], p1, 0, 0, 0); }
; }
; __device__ __forceinline__ void attn_dense_body(const bf16* __restrict__ Qb, const bf16* __restrict__ Kh, const bf16* __restrict__ Vh,
;                                                 const unsigned short* __restrict__ Gb, unsigned short* __restrict__ Yb, int seq, char* lds, const int tid) {
;     ...
;     RESC(alB); __syncthreads();
;     SBAR(); qkt(pA0, pA1, K_lds, qr, r32, hi);
;     finishSM(pB0, pB1, alB, l_reg, pa0, pa1, pa2, pa3); SBAR();
;     if (SDEPTH == 1 || j + 3 < NT) SLOAD(SE, (j + 1 + SDEPTH) * KVBLK); SBAR();
.LBB0_606:
	v_mov_b32_e32 v162, v80
	v_mov_b32_e32 v163, v81
	v_mov_b32_e32 v164, v82
	v_mov_b32_e32 v175, v83
	v_mov_b32_e32 v176, v84
	v_mov_b32_e32 v177, v85
	v_mov_b32_e32 v165, v86
	v_mov_b32_e32 v174, v87
	v_mov_b32_e32 v166, v88
	v_mov_b32_e32 v167, v89
	v_mov_b32_e32 v172, v90
	v_mov_b32_e32 v173, v91
	v_mov_b32_e32 v168, v92
	v_mov_b32_e32 v169, v93
	v_mov_b32_e32 v170, v94
	v_mov_b32_e32 v171, v95
	v_fmamk_f32 v223, v64, 0x3e0293ee, v213
	v_fmamk_f32 v224, v65, 0x3e0293ee, v213
	v_fmamk_f32 v225, v66, 0x3e0293ee, v213
	v_fmamk_f32 v226, v67, 0x3e0293ee, v213
	v_fmamk_f32 v227, v68, 0x3e0293ee, v213
	v_fmamk_f32 v216, v69, 0x3e0293ee, v213
	v_fmamk_f32 v217, v70, 0x3e0293ee, v213
	v_fmamk_f32 v218, v71, 0x3e0293ee, v213
	v_fmamk_f32 v219, v72, 0x3e0293ee, v213
	v_fmamk_f32 v220, v73, 0x3e0293ee, v213
	v_fmamk_f32 v221, v74, 0x3e0293ee, v213
	v_fmamk_f32 v222, v75, 0x3e0293ee, v213
	v_fmamk_f32 v215, v76, 0x3e0293ee, v213
	v_fmamk_f32 v228, v77, 0x3e0293ee, v213
	v_fmamk_f32 v229, v78, 0x3e0293ee, v213
	v_fmac_f32_e32 v213, 0x3e0293ee, v79
	ds_read_b128 v[64:67], v192 offset:32768
	ds_read_b128 v[68:71], v192 offset:40960
	ds_read_b128 v[242:245], v201 offset:32768
	ds_read_b128 v[246:249], v201 offset:40960
	v_add_f32_e32 v230, 0, v162
	v_add_f32_e32 v230, v163, v230
	s_waitcnt lgkmcnt(3)
	v_mfma_f32_32x32x16_bf16 v[80:95], v[64:67], v[126:129], 0
	v_add_f32_e32 v230, v164, v230
	v_add_f32_e32 v230, v175, v230
	v_add_f32_e32 v230, v176, v230
	v_add_f32_e32 v230, v177, v230
	v_add_f32_e32 v230, v165, v230
	v_add_f32_e32 v230, v174, v230
	v_add_f32_e32 v230, v166, v230
	s_waitcnt lgkmcnt(2)
	v_mfma_f32_32x32x16_bf16 v[64:79], v[68:71], v[126:129], 0
	v_add_f32_e32 v230, v167, v230
	v_add_f32_e32 v230, v172, v230
	v_add_f32_e32 v230, v173, v230
	v_exp_f32_e32 v223, v223
	v_add_f32_e32 v230, v168, v230
	v_exp_f32_e32 v224, v224
	v_add_f32_e32 v230, v169, v230
	s_waitcnt lgkmcnt(1)
	v_mfma_f32_32x32x16_bf16 v[80:95], v[242:245], v[122:125], v[80:95]
	v_exp_f32_e32 v225, v225
	v_add_f32_e32 v230, v170, v230
	v_exp_f32_e32 v226, v226
	v_add_f32_e32 v230, v171, v230
	v_exp_f32_e32 v227, v227
	v_add_f32_e32 v230, v223, v230
	v_exp_f32_e32 v216, v216
	s_waitcnt lgkmcnt(0)
	v_mfma_f32_32x32x16_bf16 v[64:79], v[246:249], v[122:125], v[64:79]
	ds_read_b128 v[242:245], v200 offset:32768
	ds_read_b128 v[246:249], v200 offset:40960
	v_add_f32_e32 v230, v224, v230
	v_exp_f32_e32 v217, v217
	v_add_f32_e32 v230, v225, v230
	v_exp_f32_e32 v218, v218
	v_add_f32_e32 v230, v226, v230
	v_exp_f32_e32 v219, v219
	s_waitcnt lgkmcnt(1)
	v_mfma_f32_32x32x16_bf16 v[80:95], v[242:245], v[134:137], v[80:95]
	v_add_f32_e32 v230, v227, v230
	v_exp_f32_e32 v220, v220
	v_add_f32_e32 v230, v216, v230
	v_exp_f32_e32 v221, v221
	v_add_f32_e32 v230, v217, v230
	v_exp_f32_e32 v222, v222
	v_add_f32_e32 v230, v218, v230
	s_waitcnt lgkmcnt(0)
	v_mfma_f32_32x32x16_bf16 v[64:79], v[246:249], v[134:137], v[64:79]
	ds_read_b128 v[242:245], v195 offset:32768
	ds_read_b128 v[246:249], v195 offset:40960
	v_exp_f32_e32 v215, v215
	v_add_f32_e32 v230, v219, v230
	v_exp_f32_e32 v228, v228
	v_add_f32_e32 v230, v220, v230
	v_exp_f32_e32 v229, v229
	v_add_f32_e32 v230, v221, v230
	s_waitcnt lgkmcnt(1)
	v_mfma_f32_32x32x16_bf16 v[80:95], v[242:245], v[130:133], v[80:95]
	v_exp_f32_e32 v213, v213
	v_add_f32_e32 v230, v222, v230
	v_add_f32_e32 v230, v215, v230
	v_add_f32_e32 v230, v228, v230
	v_add_f32_e32 v230, v229, v230
	v_add_f32_e32 v231, v213, v230
	v_mov_b32_e32 v241, v231
	s_waitcnt lgkmcnt(0)
	v_mfma_f32_32x32x16_bf16 v[64:79], v[246:249], v[130:133], v[64:79]
	ds_read_b128 v[242:245], v194 offset:32768
	ds_read_b128 v[246:249], v194 offset:40960
	v_cvt_pk_bf16_f32 v162, v162, v163
	v_cvt_pk_bf16_f32 v163, v164, v175
	v_cvt_pk_bf16_f32 v164, v176, v177
	v_cvt_pk_bf16_f32 v165, v165, v174
	v_cvt_pk_bf16_f32 v166, v166, v167
	v_cvt_pk_bf16_f32 v167, v172, v173
	s_waitcnt lgkmcnt(1)
	v_mfma_f32_32x32x16_bf16 v[80:95], v[242:245], v[118:121], v[80:95]
	v_cvt_pk_bf16_f32 v168, v168, v169
	v_cvt_pk_bf16_f32 v169, v170, v171
	v_cvt_pk_bf16_f32 v170, v223, v224
	v_cvt_pk_bf16_f32 v171, v225, v226
	v_cvt_pk_bf16_f32 v172, v227, v216
	v_cvt_pk_bf16_f32 v173, v217, v218
	v_cvt_pk_bf16_f32 v174, v219, v220
	s_waitcnt lgkmcnt(0)
	v_mfma_f32_32x32x16_bf16 v[64:79], v[246:249], v[118:121], v[64:79]
	ds_read_b128 v[242:245], v193 offset:32768
	ds_read_b128 v[246:249], v193 offset:40960
	v_cvt_pk_bf16_f32 v175, v221, v222
	v_cvt_pk_bf16_f32 v176, v215, v228
	v_cvt_pk_bf16_f32 v177, v229, v213
	v_permlane32_swap_b32_e32 v231, v241
	v_permlane32_swap_b32_e32 v162, v164
	s_waitcnt lgkmcnt(1)
	v_mfma_f32_32x32x16_bf16 v[80:95], v[242:245], v[114:117], v[80:95]
	v_permlane32_swap_b32_e32 v163, v165
	v_permlane32_swap_b32_e32 v166, v168
	v_permlane32_swap_b32_e32 v167, v169
	v_permlane32_swap_b32_e32 v170, v172
	s_waitcnt lgkmcnt(0)
	v_mfma_f32_32x32x16_bf16 v[64:79], v[246:249], v[114:117], v[64:79]
	ds_read_b128 v[242:245], v207 offset:32768
	ds_read_b128 v[246:249], v207 offset:40960
	v_permlane32_swap_b32_e32 v171, v173
	v_permlane32_swap_b32_e32 v174, v176
	v_permlane32_swap_b32_e32 v175, v177
	s_waitcnt lgkmcnt(1)
	v_mfma_f32_32x32x16_bf16 v[80:95], v[242:245], v[110:113], v[80:95]
	s_waitcnt lgkmcnt(0)
	v_mfma_f32_32x32x16_bf16 v[64:79], v[246:249], v[110:113], v[64:79]
	ds_read_b128 v[242:245], v206 offset:32768
	ds_read_b128 v[246:249], v206 offset:40960
	s_waitcnt lgkmcnt(1)
	v_mfma_f32_32x32x16_bf16 v[80:95], v[242:245], v[106:109], v[80:95]
	s_waitcnt lgkmcnt(0)
	v_mfma_f32_32x32x16_bf16 v[64:79], v[246:249], v[106:109], v[64:79]
	s_cmp_ge_u32 s40, s41
	s_cselect_b64 s[12:13], -1, 0
	s_and_b64 vcc, exec, s[12:13]
	s_cbranch_vccnz .LBB0_608
	v_add_co_u32_e32 v98, vcc, 0xffff8000, v182
	s_nop 1
	v_addc_co_u32_e32 v99, vcc, -1, v183, vcc
	v_add_co_u32_e32 v102, vcc, 0xff6f8000, v182
	s_nop 1
	v_addc_co_u32_e32 v103, vcc, -1, v183, vcc
	v_add_co_u32_e32 v142, vcc, 0xff700000, v182
	global_load_dwordx4 v[98:101], v[98:99], off
	s_nop 0
	global_load_dwordx4 v[102:105], v[102:103], off
	v_addc_co_u32_e32 v143, vcc, -1, v183, vcc
	global_load_dwordx4 v[138:141], v[182:183], off
	s_nop 0
	global_load_dwordx4 v[142:145], v[142:143], off

; #define SWAIT() do { if constexpr (SDEPTH == 2) asm volatile("s_waitcnt vmcnt(4)" ::: "memory"); else asm volatile("s_waitcnt vmcnt(0)" ::: "memory"); } while (0)
; #define RESC(a) do { if (__any((a) < 1.f)) { if (hi == 0) al_l[r32] = (a); asm volatile("s_waitcnt lgkmcnt(0)" ::: "memory"); \
;     for (int d = 0; d < 4; ++d) for (int r = 0; r < 16; ++r) o[d][r] *= al_l[crow(r, hi)]; } } while (0)
; __device__ __forceinline__ void partialSM(f32x16& p0, f32x16& p1, float& m_reg, float& mn, float& alpha) {
;     ...
;   float mnC = -mn * C;
;   for (int r = 0; r < 16; ++r) p0[r] = fmaf(p0[r], C, mnC); for (int r = 0; r < 16; ++r) p1[r] = fmaf(p1[r], C, mnC);
;   for (int r = 0; r < 16; ++r) p0[r] = __builtin_amdgcn_exp2f(p0[r]);
; }
; __device__ __forceinline__ void finishSM(f32x16& p0, f32x16& p1, float alpha, float& l_reg, bf16x8& pa0, bf16x8& pa1, bf16x8& pa2, bf16x8& pa3) {
;   for (int r = 0; r < 16; ++r) p1[r] = __builtin_amdgcn_exp2f(p1[r]);
;   float ps = 0; for (int r = 0; r < 16; ++r) ps += p0[r]; for (int r = 0; r < 16; ++r) ps += p1[r];
;   { auto rr = __builtin_amdgcn_permlane32_swap(__float_as_uint(ps), __float_as_uint(ps), false, false);
;     ps = __uint_as_float(rr[0]) + __uint_as_float(rr[1]); }
;   l_reg = l_reg * alpha + ps;
; __device__ __forceinline__ void attn_dense_body(const bf16* __restrict__ Qb, const bf16* __restrict__ Kh, const bf16* __restrict__ Vh,
;                                                 const unsigned short* __restrict__ Gb, unsigned short* __restrict__ Yb, int seq, char* lds, const int tid) {
;     ...
;     __syncthreads(); SWAIT(); SWRITE(1, SO);
;     RESC(alA); __syncthreads();
;   }
.LBB0_612:
	v_mul_f32_e32 v146, 0xbe0293ee, v210
	v_mov_b32_e32 v223, v80
	v_mov_b32_e32 v224, v81
	v_mov_b32_e32 v225, v82
	v_mov_b32_e32 v227, v83
	v_mov_b32_e32 v229, v84
	v_mov_b32_e32 v230, v85
	v_mov_b32_e32 v226, v86
	v_mov_b32_e32 v228, v87
	v_mov_b32_e32 v215, v88
	v_mov_b32_e32 v217, v89
	v_mov_b32_e32 v219, v90
	v_mov_b32_e32 v221, v91
	v_mov_b32_e32 v216, v92
	v_mov_b32_e32 v218, v93
	v_mov_b32_e32 v220, v94
	v_mov_b32_e32 v222, v95
	v_pk_fma_f32 v[176:177], v[64:65], s[84:85], v[146:147] op_sel_hi:[1,0,0]
	v_add_f32_e32 v64, v211, v212
	v_fmac_f32_e32 v64, v209, v190
	v_add_f32_e32 v190, v231, v241
	v_pk_fma_f32 v[174:175], v[66:67], s[84:85], v[146:147] op_sel_hi:[1,0,0]
	v_pk_fma_f32 v[170:171], v[68:69], s[84:85], v[146:147] op_sel_hi:[1,0,0]
	v_pk_fma_f32 v[166:167], v[70:71], s[84:85], v[146:147] op_sel_hi:[1,0,0]
	v_pk_fma_f32 v[164:165], v[72:73], s[84:85], v[146:147] op_sel_hi:[1,0,0]
	v_pk_fma_f32 v[172:173], v[74:75], s[84:85], v[146:147] op_sel_hi:[1,0,0]
	v_pk_fma_f32 v[168:169], v[76:77], s[84:85], v[146:147] op_sel_hi:[1,0,0]
	v_pk_fma_f32 v[162:163], v[78:79], s[84:85], v[146:147] op_sel_hi:[1,0,0]
	v_fmac_f32_e32 v190, v64, v214
	s_add_i32 s40, s40, 2
	v_lshl_add_u64 v[182:183], v[182:183], 0, s[82:83]
	s_and_b64 vcc, exec, s[12:13]
	s_cbranch_vccnz .LBB0_614
	v_mov_b32_e32 v209, v213
	s_branch .LBB0_602
